# v86 + HGRN2: next chunk's v loads issued at the start of step 4 behind the gate loads; no loads before the step-2 barrier; step-5 waits leave them in flight
# speedup vs baseline: 1.0098x; 1.0098x over previous
.LBB0_1168:
	s_or_b64 exec, exec, s[6:7]
	s_waitcnt lgkmcnt(0)
	ds_read_b128 v[114:117], v150 offset:52224
	ds_read_b128 v[118:121], v150 offset:52288
	v_add_u32_e32 v67, v137, v133
	ds_read_b128 v[160:163], v151
	ds_read_b128 v[164:167], v67
	ds_read_b128 v[168:171], v67 offset:2304
	ds_read_b128 v[172:175], v67 offset:64
	ds_read_b128 v[176:179], v67 offset:2368
	v_ashrrev_i32_e32 v67, 31, v66
	s_waitcnt lgkmcnt(4)
	v_pk_mul_f32 v[18:19], v[18:19], v[160:161]
	v_pk_mul_f32 v[20:21], v[20:21], v[162:163]
	v_pk_mul_f32 v[30:31], v[30:31], v[160:161]
	v_pk_mul_f32 v[32:33], v[32:33], v[162:163]
	s_waitcnt lgkmcnt(3)
	v_mfma_f32_16x16x32_bf16 v[18:21], v[114:117], v[164:167], v[18:21]
	s_waitcnt lgkmcnt(2)
	v_mfma_f32_16x16x32_bf16 v[30:33], v[114:117], v[168:171], v[30:33]
	s_waitcnt lgkmcnt(1)
	v_mfma_f32_16x16x32_bf16 v[18:21], v[118:121], v[172:175], v[18:21]
	s_waitcnt lgkmcnt(0)
	v_mfma_f32_16x16x32_bf16 v[30:33], v[118:121], v[176:179], v[30:33]
	ds_read_b128 v[164:167], v152
	ds_read_b128 v[168:171], v152 offset:2304
	ds_read_b128 v[172:175], v152 offset:64
	ds_read_b128 v[176:179], v152 offset:2368
	v_pk_mul_f32 v[34:35], v[34:35], v[160:161]
	v_pk_mul_f32 v[36:37], v[36:37], v[162:163]
	v_pk_mul_f32 v[38:39], v[38:39], v[160:161]
	v_pk_mul_f32 v[40:41], v[40:41], v[162:163]
	s_waitcnt lgkmcnt(3)
	v_mfma_f32_16x16x32_bf16 v[34:37], v[114:117], v[164:167], v[34:37]
	s_waitcnt lgkmcnt(2)
	v_mfma_f32_16x16x32_bf16 v[38:41], v[114:117], v[168:171], v[38:41]
	s_waitcnt lgkmcnt(1)
	v_mfma_f32_16x16x32_bf16 v[34:37], v[118:121], v[172:175], v[34:37]
	s_waitcnt lgkmcnt(0)
	v_mfma_f32_16x16x32_bf16 v[38:41], v[118:121], v[176:179], v[38:41]
	ds_read_b128 v[164:167], v153
	ds_read_b128 v[168:171], v153 offset:2304
	ds_read_b128 v[172:175], v153 offset:64
	ds_read_b128 v[176:179], v153 offset:2368
	v_pk_mul_f32 v[42:43], v[42:43], v[160:161]
	v_pk_mul_f32 v[44:45], v[44:45], v[162:163]
	v_pk_mul_f32 v[50:51], v[50:51], v[160:161]
	v_pk_mul_f32 v[52:53], v[52:53], v[162:163]
	s_waitcnt lgkmcnt(3)
	v_mfma_f32_16x16x32_bf16 v[42:45], v[114:117], v[164:167], v[42:45]
	s_waitcnt lgkmcnt(2)
	v_mfma_f32_16x16x32_bf16 v[50:53], v[114:117], v[168:171], v[50:53]
	s_waitcnt lgkmcnt(1)
	v_mfma_f32_16x16x32_bf16 v[42:45], v[118:121], v[172:175], v[42:45]
	s_waitcnt lgkmcnt(0)
	v_mfma_f32_16x16x32_bf16 v[50:53], v[118:121], v[176:179], v[50:53]
	ds_read_b128 v[164:167], v154
	ds_read_b128 v[168:171], v154 offset:2304
	ds_read_b128 v[172:175], v154 offset:64
	ds_read_b128 v[176:179], v154 offset:2368
	v_pk_mul_f32 v[46:47], v[46:47], v[160:161]
	v_pk_mul_f32 v[48:49], v[48:49], v[162:163]
	v_pk_mul_f32 v[54:55], v[54:55], v[160:161]
	v_pk_mul_f32 v[56:57], v[56:57], v[162:163]
	s_waitcnt lgkmcnt(3)
	v_mfma_f32_16x16x32_bf16 v[46:49], v[114:117], v[164:167], v[46:49]
	s_waitcnt lgkmcnt(0)
	s_barrier
	v_mfma_f32_16x16x32_bf16 v[54:57], v[114:117], v[168:171], v[54:57]
	ds_read2st64_b32 v[114:115], v136 offset1:1
	v_lshlrev_b64 v[66:67], 13, v[66:67]
	s_waitcnt vmcnt(5)
	v_lshlrev_b32_e32 v116, 16, v64
	v_and_b32_e32 v117, 0xffff0000, v64
	v_lshl_add_u64 v[66:67], s[4:5], 0, v[66:67]
	s_waitcnt lgkmcnt(0)
	v_add_f32_e32 v114, v114, v115
	v_fmamk_f32 v114, v114, 0x3c000000, v197
	v_cmp_gt_f32_e32 vcc, s81, v114
	v_mul_f32_e32 v115, 0x4b800000, v114
	v_lshl_add_u64 v[66:67], v[66:67], 0, s[36:37]
	v_cndmask_b32_e32 v114, v114, v115, vcc
	v_rsq_f32_e32 v114, v114
	s_mov_b64 s[6:7], 0x29401000
	v_lshl_add_u64 v[66:67], v[66:67], 0, s[6:7]
	v_mfma_f32_16x16x32_bf16 v[46:49], v[118:121], v[172:175], v[46:49]
	v_mul_f32_e32 v115, 0x45800000, v114
	v_cndmask_b32_e32 v114, v114, v115, vcc
	v_pk_mul_f32 v[70:71], v[70:71], v[114:115] op_sel_hi:[1,0]
	v_pk_mul_f32 v[68:69], v[68:69], v[114:115] op_sel_hi:[1,0]
	v_pk_mul_f32 v[70:71], v[2:3], v[70:71]
	v_pk_mul_f32 v[68:69], v[4:5], v[68:69]
	v_pk_mul_f32 v[70:71], v[70:71], v[116:117]
	v_mfma_f32_16x16x32_bf16 v[54:57], v[118:121], v[176:179], v[54:57]
	v_cvt_pk_bf16_f32 v64, v70, v71
	v_lshlrev_b32_e32 v70, 16, v65
	v_and_b32_e32 v71, 0xffff0000, v65
	v_pk_mul_f32 v[68:69], v[68:69], v[70:71]
	s_waitcnt vmcnt(4)
	v_lshlrev_b32_e32 v70, 16, v62
	v_cvt_pk_bf16_f32 v65, v68, v69
	v_lshl_add_u64 v[68:69], v[94:95], 1, v[66:67]
	global_store_dwordx2 v[68:69], v[64:65], off
	v_pk_mul_f32 v[64:65], v[104:105], v[114:115] op_sel_hi:[1,0]
	v_and_b32_e32 v71, 0xffff0000, v62
	v_pk_mul_f32 v[64:65], v[6:7], v[64:65]
	v_pk_mul_f32 v[68:69], v[72:73], v[114:115] op_sel_hi:[1,0]
	v_pk_mul_f32 v[64:65], v[64:65], v[70:71]
	v_pk_mul_f32 v[68:69], v[8:9], v[68:69]
	v_cvt_pk_bf16_f32 v62, v64, v65
	v_lshlrev_b32_e32 v64, 16, v63
	v_and_b32_e32 v65, 0xffff0000, v63
	v_pk_mul_f32 v[64:65], v[68:69], v[64:65]
	s_waitcnt vmcnt(4)
	v_lshlrev_b32_e32 v68, 16, v60
	v_cvt_pk_bf16_f32 v63, v64, v65
	v_lshl_add_u64 v[64:65], v[98:99], 1, v[66:67]
	global_store_dwordx2 v[64:65], v[62:63], off offset:32
	v_pk_mul_f32 v[62:63], v[108:109], v[114:115] op_sel_hi:[1,0]
	v_and_b32_e32 v69, 0xffff0000, v60
	v_pk_mul_f32 v[62:63], v[10:11], v[62:63]
	v_pk_mul_f32 v[66:67], v[106:107], v[114:115] op_sel_hi:[1,0]
	v_pk_mul_f32 v[62:63], v[62:63], v[68:69]
	v_pk_mul_f32 v[66:67], v[12:13], v[66:67]
	v_cvt_pk_bf16_f32 v60, v62, v63
	v_lshlrev_b32_e32 v62, 16, v61
	v_and_b32_e32 v63, 0xffff0000, v61
	v_pk_mul_f32 v[62:63], v[66:67], v[62:63]
	s_waitcnt vmcnt(4)
	v_lshlrev_b32_e32 v66, 16, v58
	v_cvt_pk_bf16_f32 v61, v62, v63
	global_store_dwordx2 v[64:65], v[60:61], off offset:64
	v_pk_mul_f32 v[60:61], v[112:113], v[114:115] op_sel_hi:[1,0]
	v_and_b32_e32 v67, 0xffff0000, v58
	v_pk_mul_f32 v[60:61], v[14:15], v[60:61]
	v_pk_mul_f32 v[62:63], v[110:111], v[114:115] op_sel_hi:[1,0]
	v_pk_mul_f32 v[60:61], v[60:61], v[66:67]
	v_pk_mul_f32 v[62:63], v[16:17], v[62:63]
	v_cvt_pk_bf16_f32 v58, v60, v61
	v_lshlrev_b32_e32 v60, 16, v59
	v_and_b32_e32 v61, 0xffff0000, v59
	v_pk_mul_f32 v[60:61], v[62:63], v[60:61]
	s_cmp_lg_u32 s3, 32
	v_cvt_pk_bf16_f32 v59, v60, v61
	global_store_dwordx2 v[64:65], v[58:59], off offset:96
	v_cvt_pk_bf16_f32 v58, v18, v19
	v_cvt_pk_bf16_f32 v59, v20, v21
	ds_write_b64 v155, v[58:59]
	v_cvt_pk_bf16_f32 v58, v30, v31
	v_cvt_pk_bf16_f32 v59, v32, v33
	ds_write_b64 v155, v[58:59] offset:4352
	v_cvt_pk_bf16_f32 v58, v34, v35
	v_cvt_pk_bf16_f32 v59, v36, v37
	ds_write_b64 v155, v[58:59] offset:8704
	v_cvt_pk_bf16_f32 v58, v38, v39
	v_cvt_pk_bf16_f32 v59, v40, v41
	ds_write_b64 v155, v[58:59] offset:13056
	v_cvt_pk_bf16_f32 v58, v42, v43
	v_cvt_pk_bf16_f32 v59, v44, v45
	ds_write_b64 v155, v[58:59] offset:17408
	v_cvt_pk_bf16_f32 v58, v50, v51
	v_cvt_pk_bf16_f32 v59, v52, v53
	ds_write_b64 v155, v[58:59] offset:21760
	v_cvt_pk_bf16_f32 v58, v46, v47
	v_cvt_pk_bf16_f32 v59, v48, v49
	ds_write_b64 v155, v[58:59] offset:26112
	v_cvt_pk_bf16_f32 v58, v54, v55
	v_cvt_pk_bf16_f32 v59, v56, v57
	s_mov_b32 s2, s3
	ds_write_b64 v155, v[58:59] offset:30464
	s_cbranch_scc0 .LBB0_1179

.LBB0_1173:
	v_readlane_b32 s6, v254, 18
	v_readlane_b32 s7, v254, 19
	s_mul_i32 s3, s20, 0x880
	s_nop 0
	v_cndmask_b32_e64 v123, v123, 0, s[6:7]
	v_cndmask_b32_e64 v122, v122, 0, s[6:7]
	v_readlane_b32 s6, v254, 26
	v_pk_add_f32 v[72:73], v[72:73], v[122:123]
	v_readlane_b32 s7, v254, 27
	s_nop 1
	v_cndmask_b32_e64 v73, v123, v73, s[6:7]
	v_cndmask_b32_e64 v72, v122, v72, s[6:7]
	v_readlane_b32 s6, v254, 28
	v_pk_add_f32 v[66:67], v[66:67], v[72:73]
	v_readlane_b32 s7, v254, 29
	s_nop 1
	v_cndmask_b32_e64 v67, v73, v67, s[6:7]
	v_cndmask_b32_e64 v66, v72, v66, s[6:7]
	v_readlane_b32 s6, v254, 30
	v_pk_add_f32 v[68:69], v[68:69], v[66:67]
	v_readlane_b32 s7, v254, 31
	s_nop 1
	v_cndmask_b32_e64 v67, v67, v69, s[6:7]
	v_cndmask_b32_e64 v66, v66, v68, s[6:7]
	v_readlane_b32 s6, v254, 32
	v_pk_add_f32 v[62:63], v[62:63], v[66:67]
	v_readlane_b32 s7, v254, 33
	v_and_b32_e32 v69, 0xffff0000, v125
	v_lshlrev_b32_e32 v68, 16, v125
	v_cndmask_b32_e64 v63, v67, v63, s[6:7]
	v_cndmask_b32_e64 v62, v66, v62, s[6:7]
	v_readlane_b32 s6, v254, 34
	v_pk_add_f32 v[64:65], v[64:65], v[62:63]
	v_readlane_b32 s7, v254, 35
	v_lshlrev_b32_e32 v66, 16, v75
	v_and_b32_e32 v67, 0xffff0000, v75
	s_mov_b32 s10, s8
	s_mul_i32 s10, s10, 0x6000
	s_mov_b32 s11, 0
	v_lshl_add_u64 v[238:239], v[78:79], 0, s[10:11]
	global_load_dword v75, v[238:239], off nt
	s_add_u32 s10, s10, 0x1000
	v_lshl_add_u64 v[240:241], v[78:79], 0, s[10:11]
	global_load_dword v125, v[240:241], off nt
	v_cndmask_b32_e64 v63, v63, v65, s[6:7]
	v_cndmask_b32_e64 v62, v62, v64, s[6:7]
	v_readlane_b32 s6, v254, 36
	v_pk_add_f32 v[58:59], v[58:59], v[62:63]
	v_readlane_b32 s7, v254, 37
	s_nop 1
	v_cndmask_b32_e64 v59, v63, v59, s[6:7]
	v_cndmask_b32_e64 v58, v62, v58, s[6:7]
	v_readlane_b32 s6, v254, 40
	v_pk_add_f32 v[60:61], v[60:61], v[58:59]
	v_readlane_b32 s7, v254, 41
	s_nop 1
	v_cndmask_b32_e64 v58, v58, v60, s[6:7]
	v_sub_f32_e32 v60, v120, v70
	v_cndmask_b32_e64 v59, v59, v61, s[6:7]
	v_exp_f32_e32 v64, v60
	v_sub_f32_e32 v60, v121, v71
	v_exp_f32_e32 v65, v60
	v_pk_add_f32 v[60:61], v[118:119], v[58:59]
	s_nop 0
	v_pk_add_f32 v[62:63], v[60:61], v[70:71] neg_lo:[0,1] neg_hi:[0,1]
	v_exp_f32_e32 v60, v60
	v_min_f32_e32 v73, 0x42e60000, v63
	v_min_f32_e64 v63, -v63, s14
	v_min_f32_e32 v72, 0x42e60000, v62
	v_min_f32_e64 v62, -v62, s14
	v_exp_f32_e32 v63, v63
	v_exp_f32_e32 v72, v72
	v_exp_f32_e32 v73, v73
	v_exp_f32_e32 v62, v62
	v_exp_f32_e32 v61, v61
	v_mul_f32_e32 v63, v63, v69
	v_add_u32_e32 v69, s3, v0
	v_mul_f32_e32 v60, v60, v66
	v_mul_f32_e32 v72, v72, v66
	v_mul_f32_e32 v73, v73, v67
	v_mul_f32_e32 v62, v62, v68
	v_cvt_pk_bf16_f32 v68, v72, v73
	ds_write_b32 v69, v68
	v_mul_f32_e32 v61, v61, v67
	v_cvt_pk_bf16_f32 v60, v60, v61
	ds_write_b32 v69, v60 offset:17408
	v_cvt_pk_bf16_f32 v60, v62, v63
	ds_write_b32 v69, v60 offset:34816
	v_pk_add_f32 v[60:61], v[116:117], v[58:59]
	v_mul_f32_e32 v66, v64, v62
	v_mul_f32_e32 v67, v63, v65
	v_pk_add_f32 v[62:63], v[60:61], v[70:71] neg_lo:[0,1] neg_hi:[0,1]
	v_exp_f32_e32 v60, v60
	v_min_f32_e32 v117, 0x42e60000, v62
	v_min_f32_e32 v118, 0x42e60000, v63
	v_min_f32_e64 v62, -v62, s14
	v_exp_f32_e32 v117, v117
	v_exp_f32_e32 v118, v118
	v_exp_f32_e32 v62, v62
	v_min_f32_e64 v63, -v63, s14
	v_exp_f32_e32 v61, v61
	v_exp_f32_e32 v63, v63
	v_lshlrev_b32_e32 v68, 16, v126
	v_and_b32_e32 v72, 0xffff0000, v126
	v_lshlrev_b32_e32 v73, 16, v127
	v_mul_f32_e32 v60, v60, v68
	v_and_b32_e32 v116, 0xffff0000, v127
	s_or_b32 s10, s8, 1
	s_mul_i32 s10, s10, 0x6000
	s_mov_b32 s11, 0
	v_lshl_add_u64 v[238:239], v[78:79], 0, s[10:11]
	global_load_dword v126, v[238:239], off nt
	s_add_u32 s10, s10, 0x1000
	v_lshl_add_u64 v[240:241], v[78:79], 0, s[10:11]
	global_load_dword v127, v[240:241], off nt
	v_mul_f32_e32 v117, v117, v68
	v_mul_f32_e32 v118, v118, v72
	v_mul_f32_e32 v62, v62, v73
	v_cvt_pk_bf16_f32 v73, v117, v118
	ds_write_b32 v69, v73 offset:272
	v_mul_f32_e32 v61, v61, v72
	v_cvt_pk_bf16_f32 v60, v60, v61
	v_mul_f32_e32 v63, v63, v116
	ds_write_b32 v69, v60 offset:17680
	v_cvt_pk_bf16_f32 v60, v62, v63
	ds_write_b32 v69, v60 offset:35088
	v_pk_add_f32 v[60:61], v[114:115], v[58:59]
	v_mul_f32_e32 v68, v64, v62
	v_mul_f32_e32 v72, v63, v65
	v_pk_add_f32 v[62:63], v[60:61], v[70:71] neg_lo:[0,1] neg_hi:[0,1]
	v_exp_f32_e32 v60, v60
	v_min_f32_e32 v117, 0x42e60000, v62
	v_min_f32_e32 v118, 0x42e60000, v63
	v_min_f32_e64 v62, -v62, s14
	v_exp_f32_e32 v117, v117
	v_exp_f32_e32 v118, v118
	v_exp_f32_e32 v62, v62
	v_min_f32_e64 v63, -v63, s14
	v_exp_f32_e32 v61, v61
	v_exp_f32_e32 v63, v63
	v_lshlrev_b32_e32 v73, 16, v128
	v_and_b32_e32 v114, 0xffff0000, v128
	v_lshlrev_b32_e32 v115, 16, v129
	v_mul_f32_e32 v60, v60, v73
	v_and_b32_e32 v116, 0xffff0000, v129
	s_or_b32 s10, s8, 2
	s_mul_i32 s10, s10, 0x6000
	s_mov_b32 s11, 0
	v_lshl_add_u64 v[238:239], v[78:79], 0, s[10:11]
	global_load_dword v128, v[238:239], off nt
	s_add_u32 s10, s10, 0x1000
	v_lshl_add_u64 v[240:241], v[78:79], 0, s[10:11]
	global_load_dword v129, v[240:241], off nt
	v_mul_f32_e32 v117, v117, v73
	v_mul_f32_e32 v118, v118, v114
	v_mul_f32_e32 v62, v62, v115
	v_cvt_pk_bf16_f32 v115, v117, v118
	ds_write_b32 v69, v115 offset:544
	v_mul_f32_e32 v61, v61, v114
	v_cvt_pk_bf16_f32 v60, v60, v61
	v_mul_f32_e32 v63, v63, v116
	ds_write_b32 v69, v60 offset:17952
	v_cvt_pk_bf16_f32 v60, v62, v63
	ds_write_b32 v69, v60 offset:35360
	v_pk_add_f32 v[60:61], v[112:113], v[58:59]
	v_mul_f32_e32 v73, v64, v62
	v_mul_f32_e32 v114, v63, v65
	v_pk_add_f32 v[62:63], v[60:61], v[70:71] neg_lo:[0,1] neg_hi:[0,1]
	v_exp_f32_e32 v60, v60
	v_min_f32_e32 v117, 0x42e60000, v62
	v_min_f32_e32 v118, 0x42e60000, v63
	v_min_f32_e64 v62, -v62, s14
	v_exp_f32_e32 v117, v117
	v_exp_f32_e32 v118, v118
	v_exp_f32_e32 v62, v62
	v_min_f32_e64 v63, -v63, s14
	v_exp_f32_e32 v61, v61
	v_exp_f32_e32 v63, v63
	v_lshlrev_b32_e32 v112, 16, v130
	v_and_b32_e32 v113, 0xffff0000, v130
	v_lshlrev_b32_e32 v115, 16, v131
	v_mul_f32_e32 v60, v60, v112
	v_and_b32_e32 v116, 0xffff0000, v131
	s_or_b32 s10, s8, 3
	s_mul_i32 s10, s10, 0x6000
	s_mov_b32 s11, 0
	v_lshl_add_u64 v[238:239], v[78:79], 0, s[10:11]
	global_load_dword v130, v[238:239], off nt
	s_add_u32 s10, s10, 0x1000
	v_lshl_add_u64 v[240:241], v[78:79], 0, s[10:11]
	global_load_dword v131, v[240:241], off nt
	v_mul_f32_e32 v117, v117, v112
	v_mul_f32_e32 v118, v118, v113
	v_mul_f32_e32 v62, v62, v115
	v_cvt_pk_bf16_f32 v115, v117, v118
	ds_write_b32 v69, v115 offset:816
	v_mul_f32_e32 v61, v61, v113
	v_cvt_pk_bf16_f32 v60, v60, v61
	v_mul_f32_e32 v63, v63, v116
	ds_write_b32 v69, v60 offset:18224
	v_cvt_pk_bf16_f32 v60, v62, v63
	ds_write_b32 v69, v60 offset:35632
	v_pk_add_f32 v[60:61], v[110:111], v[58:59]
	v_mul_f32_e32 v112, v64, v62
	v_mul_f32_e32 v113, v63, v65
	v_pk_add_f32 v[62:63], v[60:61], v[70:71] neg_lo:[0,1] neg_hi:[0,1]
	v_exp_f32_e32 v60, v60
	v_min_f32_e32 v117, 0x42e60000, v62
	v_min_f32_e32 v118, 0x42e60000, v63
	v_min_f32_e64 v62, -v62, s14
	v_exp_f32_e32 v117, v117
	v_exp_f32_e32 v118, v118
	v_exp_f32_e32 v62, v62
	v_min_f32_e64 v63, -v63, s14
	v_exp_f32_e32 v61, v61
	v_exp_f32_e32 v63, v63
	v_lshlrev_b32_e32 v110, 16, v140
	v_and_b32_e32 v111, 0xffff0000, v140
	v_lshlrev_b32_e32 v115, 16, v142
	v_mul_f32_e32 v60, v60, v110
	v_and_b32_e32 v116, 0xffff0000, v142
	s_or_b32 s10, s8, 4
	s_mul_i32 s10, s10, 0x6000
	s_mov_b32 s11, 0
	v_lshl_add_u64 v[238:239], v[78:79], 0, s[10:11]
	global_load_dword v140, v[238:239], off nt
	s_add_u32 s10, s10, 0x1000
	v_lshl_add_u64 v[240:241], v[78:79], 0, s[10:11]
	global_load_dword v142, v[240:241], off nt
	v_mul_f32_e32 v117, v117, v110
	v_mul_f32_e32 v118, v118, v111
	v_mul_f32_e32 v62, v62, v115
	v_cvt_pk_bf16_f32 v115, v117, v118
	ds_write_b32 v69, v115 offset:1088
	v_mul_f32_e32 v61, v61, v111
	v_cvt_pk_bf16_f32 v60, v60, v61
	v_mul_f32_e32 v63, v63, v116
	ds_write_b32 v69, v60 offset:18496
	v_cvt_pk_bf16_f32 v60, v62, v63
	ds_write_b32 v69, v60 offset:35904
	v_pk_add_f32 v[60:61], v[108:109], v[58:59]
	v_mul_f32_e32 v110, v64, v62
	v_mul_f32_e32 v111, v63, v65
	v_pk_add_f32 v[62:63], v[60:61], v[70:71] neg_lo:[0,1] neg_hi:[0,1]
	v_exp_f32_e32 v60, v60
	v_min_f32_e32 v117, 0x42e60000, v62
	v_min_f32_e32 v118, 0x42e60000, v63
	v_min_f32_e64 v62, -v62, s14
	v_exp_f32_e32 v117, v117
	v_exp_f32_e32 v118, v118
	v_exp_f32_e32 v62, v62
	v_min_f32_e64 v63, -v63, s14
	v_exp_f32_e32 v61, v61
	v_exp_f32_e32 v63, v63
	v_lshlrev_b32_e32 v108, 16, v144
	v_and_b32_e32 v109, 0xffff0000, v144
	v_lshlrev_b32_e32 v115, 16, v149
	v_mul_f32_e32 v60, v60, v108
	v_and_b32_e32 v116, 0xffff0000, v149
	s_or_b32 s10, s8, 5
	s_mul_i32 s10, s10, 0x6000
	s_mov_b32 s11, 0
	v_lshl_add_u64 v[238:239], v[78:79], 0, s[10:11]
	global_load_dword v144, v[238:239], off nt
	s_add_u32 s10, s10, 0x1000
	v_lshl_add_u64 v[240:241], v[78:79], 0, s[10:11]
	global_load_dword v149, v[240:241], off nt
	v_mul_f32_e32 v117, v117, v108
	v_mul_f32_e32 v118, v118, v109
	v_mul_f32_e32 v62, v62, v115
	v_cvt_pk_bf16_f32 v115, v117, v118
	ds_write_b32 v69, v115 offset:1360
	v_mul_f32_e32 v61, v61, v109
	v_cvt_pk_bf16_f32 v60, v60, v61
	v_mul_f32_e32 v63, v63, v116
	ds_write_b32 v69, v60 offset:18768
	v_cvt_pk_bf16_f32 v60, v62, v63
	ds_write_b32 v69, v60 offset:36176
	v_pk_add_f32 v[60:61], v[106:107], v[58:59]
	v_mul_f32_e32 v108, v64, v62
	v_mul_f32_e32 v109, v63, v65
	v_pk_add_f32 v[62:63], v[60:61], v[70:71] neg_lo:[0,1] neg_hi:[0,1]
	v_exp_f32_e32 v60, v60
	v_min_f32_e32 v117, 0x42e60000, v62
	v_min_f32_e32 v118, 0x42e60000, v63
	v_min_f32_e64 v62, -v62, s14
	v_exp_f32_e32 v117, v117
	v_exp_f32_e32 v118, v118
	v_exp_f32_e32 v62, v62
	v_min_f32_e64 v63, -v63, s14
	v_exp_f32_e32 v61, v61
	v_exp_f32_e32 v63, v63
	v_lshlrev_b32_e32 v106, 16, v156
	v_and_b32_e32 v107, 0xffff0000, v156
	v_lshlrev_b32_e32 v115, 16, v157
	v_mul_f32_e32 v60, v60, v106
	v_and_b32_e32 v116, 0xffff0000, v157
	s_or_b32 s10, s8, 6
	s_mul_i32 s10, s10, 0x6000
	s_mov_b32 s11, 0
	v_lshl_add_u64 v[238:239], v[78:79], 0, s[10:11]
	global_load_dword v156, v[238:239], off nt
	s_add_u32 s10, s10, 0x1000
	v_lshl_add_u64 v[240:241], v[78:79], 0, s[10:11]
	global_load_dword v157, v[240:241], off nt
	v_mul_f32_e32 v117, v117, v106
	v_mul_f32_e32 v118, v118, v107
	v_mul_f32_e32 v62, v62, v115
	v_cvt_pk_bf16_f32 v115, v117, v118
	ds_write_b32 v69, v115 offset:1632
	v_mul_f32_e32 v61, v61, v107
	v_cvt_pk_bf16_f32 v60, v60, v61
	v_mul_f32_e32 v63, v63, v116
	ds_write_b32 v69, v60 offset:19040
	v_cvt_pk_bf16_f32 v60, v62, v63
	v_pk_add_f32 v[58:59], v[104:105], v[58:59]
	ds_write_b32 v69, v60 offset:36448
	v_pk_add_f32 v[60:61], v[58:59], v[70:71] neg_lo:[0,1] neg_hi:[0,1]
	v_exp_f32_e32 v58, v58
	v_min_f32_e32 v106, 0x42e60000, v60
	v_min_f32_e32 v107, 0x42e60000, v61
	v_min_f32_e64 v60, -v60, s14
	v_exp_f32_e32 v106, v106
	v_exp_f32_e32 v107, v107
	v_exp_f32_e32 v60, v60
	v_min_f32_e64 v61, -v61, s14
	v_exp_f32_e32 v59, v59
	v_exp_f32_e32 v61, v61
	v_lshlrev_b32_e32 v70, 16, v158
	v_and_b32_e32 v71, 0xffff0000, v158
	v_lshlrev_b32_e32 v104, 16, v159
	v_mul_f32_e32 v58, v58, v70
	v_and_b32_e32 v105, 0xffff0000, v159
	s_or_b32 s10, s8, 7
	s_mul_i32 s10, s10, 0x6000
	s_mov_b32 s11, 0
	v_lshl_add_u64 v[238:239], v[78:79], 0, s[10:11]
	global_load_dword v158, v[238:239], off nt
	s_add_u32 s10, s10, 0x1000
	v_lshl_add_u64 v[240:241], v[78:79], 0, s[10:11]
	global_load_dword v159, v[240:241], off nt
	v_mul_f32_e32 v106, v106, v70
	v_mul_f32_e32 v107, v107, v71
	v_mul_f32_e32 v60, v60, v104
	v_cvt_pk_bf16_f32 v104, v106, v107
	ds_write_b32 v69, v104 offset:1904
	v_mul_f32_e32 v59, v59, v71
	v_cvt_pk_bf16_f32 v58, v58, v59
	v_mul_f32_e32 v61, v61, v105
	ds_write_b32 v69, v58 offset:19312
	v_cvt_pk_bf16_f32 v58, v60, v61
	ds_write_b32 v69, v58 offset:36720
	v_cvt_pk_bf16_f32 v58, v66, v68
	v_mul_f32_e32 v62, v64, v62
	v_mul_f32_e32 v63, v63, v65
	v_mul_f32_e32 v64, v64, v60
	v_mul_f32_e32 v65, v61, v65
	v_cvt_pk_bf16_f32 v59, v73, v112
	v_cvt_pk_bf16_f32 v60, v110, v108
	v_cvt_pk_bf16_f32 v61, v62, v64
	ds_write_b128 v143, v[58:61] offset:52224
	v_cvt_pk_bf16_f32 v58, v67, v72
	s_add_i32 s3, s2, 1
	v_cvt_pk_bf16_f32 v59, v114, v113
	v_cvt_pk_bf16_f32 v60, v111, v109
	v_cvt_pk_bf16_f32 v61, v63, v65
	ds_write_b128 v143, v[58:61] offset:52368
	v_add_u32_e32 v58, s19, v74
	s_cmp_eq_u32 s2, 31
	ds_write_b16 v58, v22
	ds_write_b16_d16_hi v58, v22 offset:144
	ds_write_b16 v58, v23 offset:288
	ds_write_b16_d16_hi v58, v23 offset:432
	ds_write_b16 v58, v24 offset:576
	ds_write_b16_d16_hi v58, v24 offset:720
	ds_write_b16 v58, v25 offset:864
	ds_write_b16_d16_hi v58, v25 offset:1008
	s_waitcnt vmcnt(28)
	ds_write_b16 v58, v26 offset:1152
	ds_write_b16_d16_hi v58, v26 offset:1296
	ds_write_b16 v58, v27 offset:1440
	ds_write_b16_d16_hi v58, v27 offset:1584
	ds_write_b16 v58, v28 offset:1728
	ds_write_b16_d16_hi v58, v28 offset:1872
	ds_write_b16 v58, v29 offset:2016
	ds_write_b16_d16_hi v58, v29 offset:2160
.LBB0_1175:
	v_readlane_b32 s6, v254, 22
	v_readlane_b32 s7, v254, 23
	s_andn2_b64 vcc, exec, s[6:7]
	v_mov_b32_e32 v58, v141
	v_mov_b32_e32 v59, v139
	s_mov_b32 s6, s20
	s_waitcnt lgkmcnt(0)
	s_barrier
	s_cbranch_vccnz .LBB0_1177

.LBB0_1177:
	v_lshl_add_u32 v66, s2, 6, v138
	v_mov_b64_e32 v[58:59], s[0:1]
	v_mad_i64_i32 v[58:59], s[6:7], v66, s28, v[58:59]
	v_readlane_b32 s6, v254, 47
	v_lshl_add_u64 v[58:59], v[58:59], 0, s[36:37]
	v_readlane_b32 s7, v254, 48
	v_lshl_add_u64 v[58:59], v[88:89], 1, v[58:59]
	s_lshl_b32 s6, s6, 1
	s_mov_b32 s7, s37
	v_lshl_add_u64 v[58:59], v[58:59], 0, s[6:7]
	s_mov_b64 s[6:7], 0x5000
	v_lshl_add_u64 v[68:69], v[58:59], 0, s[6:7]
	v_add_co_u32_e32 v58, vcc, s13, v58
	s_waitcnt lgkmcnt(0)
	s_nop 0
	v_addc_co_u32_e32 v59, vcc, 0, v59, vcc
	s_barrier
	global_load_dwordx2 v[64:65], v[58:59], off
	global_load_dwordx2 v[62:63], v[68:69], off offset:32
	global_load_dwordx2 v[60:61], v[68:69], off offset:64
	s_nop 0
	global_load_dwordx2 v[58:59], v[68:69], off offset:96
	s_add_i32 s6, s2, 1
	s_min_u32 s6, s6, 31
	s_mul_i32 s6, s6, 0x180000
	s_mov_b32 s7, s37
	v_lshl_add_u64 v[240:241], v[84:85], 0, s[6:7]
	global_load_dwordx4 v[22:25], v[240:241], off
	global_load_dwordx4 v[26:29], v[240:241], off offset:16
	ds_read_b128 v[110:113], v145
	ds_read_b128 v[114:117], v145 offset:64
	ds_read_b128 v[118:121], v146 offset:17408
	ds_read_b128 v[160:163], v146 offset:17472
	ds_read_b128 v[164:167], v146 offset:17536
	ds_read_b128 v[168:171], v146 offset:17600
	ds_read_b128 v[68:71], v147
	ds_read_b128 v[104:107], v147 offset:64
	ds_read_b128 v[172:175], v148
	ds_read_b128 v[176:179], v148 offset:64
	ds_read_b128 v[188:191], v148 offset:128
	ds_read_b128 v[192:195], v148 offset:192
	s_waitcnt lgkmcnt(5)
	v_mfma_f32_16x16x32_bf16 v[68:71], v[68:71], v[110:113], 0
	s_waitcnt lgkmcnt(3)
	v_mfma_f32_16x16x32_bf16 v[172:175], v[172:175], v[118:121], 0
	v_mfma_f32_16x16x32_bf16 v[68:71], v[104:107], v[114:117], v[68:71]
	s_waitcnt lgkmcnt(2)
	v_mfma_f32_16x16x32_bf16 v[104:107], v[176:179], v[160:163], v[172:175]
	s_waitcnt lgkmcnt(1)
	v_mfma_f32_16x16x32_bf16 v[70:73], v[188:191], v[164:167], v[68:71]
	s_waitcnt lgkmcnt(0)
	v_mfma_f32_16x16x32_bf16 v[104:107], v[192:195], v[168:171], v[104:107]
	s_nop 7
	v_pk_add_f32 v[68:69], v[72:73], v[106:107]
	v_pk_add_f32 v[70:71], v[70:71], v[104:105]
	ds_read_b128 v[104:107], v147 offset:2304
	ds_read_b128 v[172:175], v147 offset:2368
	ds_read_b128 v[176:179], v148 offset:4352
	ds_read_b128 v[188:191], v148 offset:4416
	ds_read_b128 v[192:195], v148 offset:4480
	ds_read_b128 v[206:209], v148 offset:4544
	s_waitcnt lgkmcnt(5)
	v_mfma_f32_16x16x32_bf16 v[104:107], v[104:107], v[110:113], 0
	s_waitcnt lgkmcnt(3)
	v_mfma_f32_16x16x32_bf16 v[176:179], v[176:179], v[118:121], 0
	v_mfma_f32_16x16x32_bf16 v[104:107], v[172:175], v[114:117], v[104:107]
	s_waitcnt lgkmcnt(2)
	v_mfma_f32_16x16x32_bf16 v[172:175], v[188:191], v[160:163], v[176:179]
	s_waitcnt lgkmcnt(1)
	v_mfma_f32_16x16x32_bf16 v[104:107], v[192:195], v[164:167], v[104:107]
	s_waitcnt lgkmcnt(0)
	v_mfma_f32_16x16x32_bf16 v[172:175], v[206:209], v[168:171], v[172:175]
	s_nop 7
	v_pk_add_f32 v[72:73], v[106:107], v[174:175]
	v_pk_add_f32 v[104:105], v[104:105], v[172:173]
	ds_read_b128 v[106:109], v147 offset:4608
	ds_read_b128 v[172:175], v147 offset:4672
	ds_read_b128 v[176:179], v148 offset:8704
	ds_read_b128 v[188:191], v148 offset:8768
	ds_read_b128 v[192:195], v148 offset:8832
	ds_read_b128 v[206:209], v148 offset:8896
	s_waitcnt lgkmcnt(5)
	v_mfma_f32_16x16x32_bf16 v[106:109], v[106:109], v[110:113], 0
	s_waitcnt lgkmcnt(3)
	v_mfma_f32_16x16x32_bf16 v[176:179], v[176:179], v[118:121], 0
	v_mfma_f32_16x16x32_bf16 v[106:109], v[172:175], v[114:117], v[106:109]
	s_waitcnt lgkmcnt(2)
	v_mfma_f32_16x16x32_bf16 v[172:175], v[188:191], v[160:163], v[176:179]
	s_waitcnt lgkmcnt(1)
	v_mfma_f32_16x16x32_bf16 v[176:179], v[192:195], v[164:167], v[106:109]
	s_waitcnt lgkmcnt(0)
	v_mfma_f32_16x16x32_bf16 v[172:175], v[206:209], v[168:171], v[172:175]
	s_nop 7
	v_pk_add_f32 v[106:107], v[178:179], v[174:175]
	v_pk_add_f32 v[108:109], v[176:177], v[172:173]
	ds_read_b128 v[172:175], v147 offset:6912
	ds_read_b128 v[176:179], v147 offset:6976
	ds_read_b128 v[188:191], v148 offset:13056
	ds_read_b128 v[192:195], v148 offset:13120
	ds_read_b128 v[206:209], v148 offset:13184
	ds_read_b128 v[210:213], v148 offset:13248
	s_waitcnt lgkmcnt(5)
	v_mfma_f32_16x16x32_bf16 v[110:113], v[172:175], v[110:113], 0
	v_mul_f32_e32 v67, v71, v71
	v_fmac_f32_e32 v67, v70, v70
	v_fmac_f32_e32 v67, v68, v68
	s_waitcnt lgkmcnt(3)
	v_mfma_f32_16x16x32_bf16 v[118:121], v[188:191], v[118:121], 0
	v_fmac_f32_e32 v67, v69, v69
	v_mfma_f32_16x16x32_bf16 v[110:113], v[176:179], v[114:117], v[110:113]
	s_waitcnt lgkmcnt(2)
	v_mfma_f32_16x16x32_bf16 v[114:117], v[192:195], v[160:163], v[118:121]
	s_waitcnt lgkmcnt(1)
	v_mfma_f32_16x16x32_bf16 v[118:121], v[206:209], v[164:167], v[110:113]
	s_waitcnt lgkmcnt(0)
	v_mfma_f32_16x16x32_bf16 v[112:115], v[210:213], v[168:171], v[114:117]
	s_nop 7
	v_pk_add_f32 v[110:111], v[120:121], v[114:115]
	v_mul_f32_e32 v114, v105, v105
	v_fmac_f32_e32 v114, v104, v104
	v_fmac_f32_e32 v114, v72, v72
	v_fmac_f32_e32 v114, v73, v73
	v_add_f32_e32 v67, v67, v114
	v_mul_f32_e32 v114, v109, v109
	v_fmac_f32_e32 v114, v108, v108
	v_fmac_f32_e32 v114, v106, v106
	v_pk_add_f32 v[112:113], v[118:119], v[112:113]
	v_fmac_f32_e32 v114, v107, v107
	v_add_f32_e32 v67, v67, v114
	v_mul_f32_e32 v114, v113, v113
	v_fmac_f32_e32 v114, v112, v112
	v_fmac_f32_e32 v114, v110, v110
	v_fmac_f32_e32 v114, v111, v111
	v_and_b32_e32 v115, 64, v200
	v_add_f32_e32 v67, v67, v114
	v_xor_b32_e32 v114, 16, v200
	v_add_u32_e32 v115, 64, v115
	v_cmp_lt_i32_e32 vcc, v114, v115
	s_nop 1
	v_cndmask_b32_e32 v114, v200, v114, vcc
	v_lshlrev_b32_e32 v114, 2, v114
	ds_bpermute_b32 v114, v114, v67
	s_waitcnt lgkmcnt(0)
	v_add_f32_e32 v67, v67, v114
	v_xor_b32_e32 v114, 32, v200
	v_cmp_lt_i32_e32 vcc, v114, v115
	s_nop 1
	v_cndmask_b32_e32 v114, v200, v114, vcc
	v_lshlrev_b32_e32 v114, 2, v114
	ds_bpermute_b32 v114, v114, v67
	s_and_saveexec_b64 s[6:7], s[86:87]
	s_cbranch_execz .LBB0_1168
	s_waitcnt lgkmcnt(0)
	v_add_f32_e32 v67, v67, v114
	ds_write_b32 v135, v67
	s_branch .LBB0_1168
